# v113: v106 with the main loop's four operand-pointer increments moved in front of the loop-back barrier (less scalar work between the barrier release and the next segment)
# baseline (speedup 1.0000x reference)
.LBB0_394:
	s_add_i32 s13, s8, 2
	s_add_u32 s14, s2, 0x80
	s_addc_u32 s9, s3, 0
	s_add_i32 s38, 0, 0x10000
	s_cmp_eq_u32 s85, s8
	s_cselect_b32 s9, s19, s9
	s_cselect_b32 s8, s18, s14
	v_add_u32_e32 v0, s38, v237
	s_cselect_b32 s15, s21, s11
	s_cselect_b32 s14, s20, s10
	s_add_i32 s39, 0, 0x14000
	ds_read_b128 v[130:133], v0
	ds_read_b128 v[134:137], v0 offset:1024
	ds_read_b128 v[138:141], v0 offset:2048
	ds_read_b128 v[142:145], v0 offset:3072
	v_add_u32_e32 v0, s39, v237
	ds_read_b128 v[146:149], v0
	ds_read_b128 v[150:153], v0 offset:1024
	ds_read_b128 v[154:157], v0 offset:2048
	ds_read_b128 v[158:161], v0 offset:3072
	v_lshl_add_u64 v[214:215], s[2:3], 0, v[182:183]
	s_add_i32 m0, s57, 0xc000
	ds_read_b128 v[162:165], v238
	ds_read_b128 v[186:189], v238 offset:1024
	ds_read_b128 v[190:193], v238 offset:2048
	ds_read_b128 v[194:197], v238 offset:3072
	ds_read_b128 v[198:201], v238 offset:4096
	ds_read_b128 v[202:205], v238 offset:5120
	ds_read_b128 v[206:209], v238 offset:6144
	ds_read_b128 v[210:213], v238 offset:7168
	global_load_lds_dwordx4 v[214:215], off
	v_lshl_add_u64 v[214:215], s[2:3], 0, v[184:185]
	s_add_i32 m0, s57, 0xe000
	s_nop 0
	global_load_lds_dwordx4 v[214:215], off
	s_waitcnt vmcnt(8)
	s_waitcnt lgkmcnt(0)
	s_barrier
	s_nop 0
	s_waitcnt lgkmcnt(0)
	v_mfma_f32_16x16x32_bf16 v[126:129], v[130:133], v[162:165], v[126:129]
	v_mfma_f32_16x16x32_bf16 v[122:125], v[138:141], v[162:165], v[122:125]
	v_mfma_f32_16x16x32_bf16 v[110:113], v[130:133], v[190:193], v[110:113]
	v_mfma_f32_16x16x32_bf16 v[106:109], v[138:141], v[190:193], v[106:109]
	v_mfma_f32_16x16x32_bf16 v[94:97], v[130:133], v[198:201], v[94:97]
	v_mfma_f32_16x16x32_bf16 v[90:93], v[138:141], v[198:201], v[90:93]
	v_mfma_f32_16x16x32_bf16 v[78:81], v[130:133], v[206:209], v[78:81]
	v_mfma_f32_16x16x32_bf16 v[74:77], v[138:141], v[206:209], v[74:77]
	v_mfma_f32_16x16x32_bf16 v[126:129], v[134:137], v[186:189], v[126:129]
	v_mfma_f32_16x16x32_bf16 v[122:125], v[142:145], v[186:189], v[122:125]
	v_mfma_f32_16x16x32_bf16 v[110:113], v[134:137], v[194:197], v[110:113]
	v_mfma_f32_16x16x32_bf16 v[106:109], v[142:145], v[194:197], v[106:109]
	v_mfma_f32_16x16x32_bf16 v[94:97], v[134:137], v[202:205], v[94:97]
	v_mfma_f32_16x16x32_bf16 v[90:93], v[142:145], v[202:205], v[90:93]
	v_mfma_f32_16x16x32_bf16 v[78:81], v[134:137], v[210:213], v[78:81]
	v_mfma_f32_16x16x32_bf16 v[74:77], v[142:145], v[210:213], v[74:77]
	s_nop 0
	s_nop 0
	v_mfma_f32_16x16x32_bf16 v[118:121], v[146:149], v[162:165], v[118:121]
	v_mfma_f32_16x16x32_bf16 v[114:117], v[154:157], v[162:165], v[114:117]
	v_mfma_f32_16x16x32_bf16 v[102:105], v[146:149], v[190:193], v[102:105]
	v_mfma_f32_16x16x32_bf16 v[98:101], v[154:157], v[190:193], v[98:101]
	v_mfma_f32_16x16x32_bf16 v[86:89], v[146:149], v[198:201], v[86:89]
	v_mfma_f32_16x16x32_bf16 v[82:85], v[154:157], v[198:201], v[82:85]
	v_mfma_f32_16x16x32_bf16 v[70:73], v[146:149], v[206:209], v[70:73]
	v_mfma_f32_16x16x32_bf16 v[66:69], v[154:157], v[206:209], v[66:69]
	v_mfma_f32_16x16x32_bf16 v[118:121], v[150:153], v[186:189], v[118:121]
	v_mfma_f32_16x16x32_bf16 v[114:117], v[158:161], v[186:189], v[114:117]
	v_mfma_f32_16x16x32_bf16 v[102:105], v[150:153], v[194:197], v[102:105]
	v_mfma_f32_16x16x32_bf16 v[98:101], v[158:161], v[194:197], v[98:101]
	v_mfma_f32_16x16x32_bf16 v[86:89], v[150:153], v[202:205], v[86:89]
	v_mfma_f32_16x16x32_bf16 v[82:85], v[158:161], v[202:205], v[82:85]
	v_mfma_f32_16x16x32_bf16 v[70:73], v[150:153], v[210:213], v[70:73]
	v_mfma_f32_16x16x32_bf16 v[66:69], v[158:161], v[210:213], v[66:69]
	s_nop 0
	s_barrier
	s_add_i32 s38, s38, s56
	v_lshl_add_u64 v[214:215], s[14:15], 0, v[176:177]
	s_mov_b32 m0, s38
	ds_read_b128 v[162:165], v238 offset:16384
	ds_read_b128 v[186:189], v238 offset:17408
	ds_read_b128 v[190:193], v238 offset:18432
	ds_read_b128 v[194:197], v238 offset:19456
	ds_read_b128 v[198:201], v238 offset:20480
	ds_read_b128 v[202:205], v238 offset:21504
	ds_read_b128 v[206:209], v238 offset:22528
	ds_read_b128 v[210:213], v238 offset:23552
	global_load_lds_dwordx4 v[214:215], off
	s_add_i32 m0, s38, 0x2000
	v_lshl_add_u64 v[216:217], s[14:15], 0, v[172:173]
	s_add_u32 s14, s14, s70
	s_addc_u32 s15, s15, s71
	s_add_i32 s38, s39, s56
	global_load_lds_dwordx4 v[216:217], off
	v_lshl_add_u64 v[218:219], s[14:15], 0, v[176:177]
	s_mov_b32 m0, s38
	v_lshl_add_u64 v[220:221], s[14:15], 0, v[172:173]
	global_load_lds_dwordx4 v[218:219], off
	s_add_i32 m0, s38, 0x2000
	v_lshl_add_u64 v[222:223], s[8:9], 0, v[174:175]
	global_load_lds_dwordx4 v[220:221], off
	s_mov_b32 m0, s57
	v_lshl_add_u64 v[240:241], s[8:9], 0, v[170:171]
	global_load_lds_dwordx4 v[222:223], off
	s_mov_b32 m0, s58
	s_nop 0
	global_load_lds_dwordx4 v[240:241], off
	s_waitcnt vmcnt(8)
	s_waitcnt lgkmcnt(0)
	s_barrier
	s_nop 0
	s_waitcnt lgkmcnt(0)
	v_mfma_f32_16x16x32_bf16 v[62:65], v[130:133], v[162:165], v[62:65]
	v_mfma_f32_16x16x32_bf16 v[58:61], v[138:141], v[162:165], v[58:61]
	v_mfma_f32_16x16x32_bf16 v[46:49], v[130:133], v[190:193], v[46:49]
	v_mfma_f32_16x16x32_bf16 v[42:45], v[138:141], v[190:193], v[42:45]
	v_mfma_f32_16x16x32_bf16 v[30:33], v[130:133], v[198:201], v[30:33]
	v_mfma_f32_16x16x32_bf16 v[26:29], v[138:141], v[198:201], v[26:29]
	v_mfma_f32_16x16x32_bf16 v[14:17], v[130:133], v[206:209], v[14:17]
	v_mfma_f32_16x16x32_bf16 v[10:13], v[138:141], v[206:209], v[10:13]
	v_mfma_f32_16x16x32_bf16 v[62:65], v[134:137], v[186:189], v[62:65]
	v_mfma_f32_16x16x32_bf16 v[58:61], v[142:145], v[186:189], v[58:61]
	v_mfma_f32_16x16x32_bf16 v[46:49], v[134:137], v[194:197], v[46:49]
	v_mfma_f32_16x16x32_bf16 v[42:45], v[142:145], v[194:197], v[42:45]
	v_mfma_f32_16x16x32_bf16 v[30:33], v[134:137], v[202:205], v[30:33]
	v_mfma_f32_16x16x32_bf16 v[26:29], v[142:145], v[202:205], v[26:29]
	v_mfma_f32_16x16x32_bf16 v[14:17], v[134:137], v[210:213], v[14:17]
	v_mfma_f32_16x16x32_bf16 v[10:13], v[142:145], v[210:213], v[10:13]
	s_nop 0
	s_nop 0
	v_mfma_f32_16x16x32_bf16 v[54:57], v[146:149], v[162:165], v[54:57]
	v_mfma_f32_16x16x32_bf16 v[50:53], v[154:157], v[162:165], v[50:53]
	v_mfma_f32_16x16x32_bf16 v[38:41], v[146:149], v[190:193], v[38:41]
	v_mfma_f32_16x16x32_bf16 v[34:37], v[154:157], v[190:193], v[34:37]
	v_mfma_f32_16x16x32_bf16 v[22:25], v[146:149], v[198:201], v[22:25]
	v_mfma_f32_16x16x32_bf16 v[18:21], v[154:157], v[198:201], v[18:21]
	v_mfma_f32_16x16x32_bf16 v[6:9], v[146:149], v[206:209], v[6:9]
	v_mfma_f32_16x16x32_bf16 v[2:5], v[154:157], v[206:209], v[2:5]
	v_mfma_f32_16x16x32_bf16 v[54:57], v[150:153], v[186:189], v[54:57]
	v_mfma_f32_16x16x32_bf16 v[50:53], v[158:161], v[186:189], v[50:53]
	v_mfma_f32_16x16x32_bf16 v[38:41], v[150:153], v[194:197], v[38:41]
	v_mfma_f32_16x16x32_bf16 v[34:37], v[158:161], v[194:197], v[34:37]
	v_mfma_f32_16x16x32_bf16 v[22:25], v[150:153], v[202:205], v[22:25]
	v_mfma_f32_16x16x32_bf16 v[18:21], v[158:161], v[202:205], v[18:21]
	v_mfma_f32_16x16x32_bf16 v[6:9], v[150:153], v[210:213], v[6:9]
	v_mfma_f32_16x16x32_bf16 v[2:5], v[158:161], v[210:213], v[2:5]
	s_nop 0
	s_barrier
	s_add_i32 s14, 0, 0x18000
	v_add_u32_e32 v0, s14, v237
	s_add_i32 s15, 0, 0x1c000
	ds_read_b128 v[130:133], v0
	ds_read_b128 v[134:137], v0 offset:1024
	ds_read_b128 v[138:141], v0 offset:2048
	ds_read_b128 v[142:145], v0 offset:3072
	v_add_u32_e32 v0, s15, v237
	ds_read_b128 v[146:149], v0
	ds_read_b128 v[150:153], v0 offset:1024
	ds_read_b128 v[154:157], v0 offset:2048
	ds_read_b128 v[158:161], v0 offset:3072
	s_add_u32 s8, s8, s50
	s_addc_u32 s9, s9, s51
	s_mov_b32 m0, s59
	v_lshl_add_u64 v[242:243], s[8:9], 0, v[174:175]
	ds_read_b128 v[162:165], v238 offset:32768
	ds_read_b128 v[186:189], v238 offset:33792
	ds_read_b128 v[190:193], v238 offset:34816
	ds_read_b128 v[194:197], v238 offset:35840
	ds_read_b128 v[198:201], v238 offset:36864
	ds_read_b128 v[202:205], v238 offset:37888
	ds_read_b128 v[206:209], v238 offset:38912
	ds_read_b128 v[210:213], v238 offset:39936
	global_load_lds_dwordx4 v[242:243], off
	v_lshl_add_u64 v[242:243], s[8:9], 0, v[170:171]
	s_mov_b32 m0, s60
	s_nop 0
	global_load_lds_dwordx4 v[242:243], off
	s_waitcnt vmcnt(8)
	s_waitcnt lgkmcnt(0)
	s_barrier
	s_nop 0
	s_waitcnt lgkmcnt(0)
	v_mfma_f32_16x16x32_bf16 v[126:129], v[130:133], v[162:165], v[126:129]
	v_mfma_f32_16x16x32_bf16 v[122:125], v[138:141], v[162:165], v[122:125]
	v_mfma_f32_16x16x32_bf16 v[110:113], v[130:133], v[190:193], v[110:113]
	v_mfma_f32_16x16x32_bf16 v[106:109], v[138:141], v[190:193], v[106:109]
	v_mfma_f32_16x16x32_bf16 v[94:97], v[130:133], v[198:201], v[94:97]
	v_mfma_f32_16x16x32_bf16 v[90:93], v[138:141], v[198:201], v[90:93]
	v_mfma_f32_16x16x32_bf16 v[78:81], v[130:133], v[206:209], v[78:81]
	v_mfma_f32_16x16x32_bf16 v[74:77], v[138:141], v[206:209], v[74:77]
	v_mfma_f32_16x16x32_bf16 v[126:129], v[134:137], v[186:189], v[126:129]
	v_mfma_f32_16x16x32_bf16 v[122:125], v[142:145], v[186:189], v[122:125]
	v_mfma_f32_16x16x32_bf16 v[110:113], v[134:137], v[194:197], v[110:113]
	v_mfma_f32_16x16x32_bf16 v[106:109], v[142:145], v[194:197], v[106:109]
	v_mfma_f32_16x16x32_bf16 v[94:97], v[134:137], v[202:205], v[94:97]
	v_mfma_f32_16x16x32_bf16 v[90:93], v[142:145], v[202:205], v[90:93]
	v_mfma_f32_16x16x32_bf16 v[78:81], v[134:137], v[210:213], v[78:81]
	v_mfma_f32_16x16x32_bf16 v[74:77], v[142:145], v[210:213], v[74:77]
	s_nop 0
	s_nop 0
	v_mfma_f32_16x16x32_bf16 v[118:121], v[146:149], v[162:165], v[118:121]
	v_mfma_f32_16x16x32_bf16 v[114:117], v[154:157], v[162:165], v[114:117]
	v_mfma_f32_16x16x32_bf16 v[102:105], v[146:149], v[190:193], v[102:105]
	v_mfma_f32_16x16x32_bf16 v[98:101], v[154:157], v[190:193], v[98:101]
	v_mfma_f32_16x16x32_bf16 v[86:89], v[146:149], v[198:201], v[86:89]
	v_mfma_f32_16x16x32_bf16 v[82:85], v[154:157], v[198:201], v[82:85]
	v_mfma_f32_16x16x32_bf16 v[70:73], v[146:149], v[206:209], v[70:73]
	v_mfma_f32_16x16x32_bf16 v[66:69], v[154:157], v[206:209], v[66:69]
	v_mfma_f32_16x16x32_bf16 v[118:121], v[150:153], v[186:189], v[118:121]
	v_mfma_f32_16x16x32_bf16 v[114:117], v[158:161], v[186:189], v[114:117]
	v_mfma_f32_16x16x32_bf16 v[102:105], v[150:153], v[194:197], v[102:105]
	v_mfma_f32_16x16x32_bf16 v[98:101], v[158:161], v[194:197], v[98:101]
	v_mfma_f32_16x16x32_bf16 v[86:89], v[150:153], v[202:205], v[86:89]
	v_mfma_f32_16x16x32_bf16 v[82:85], v[158:161], v[202:205], v[82:85]
	v_mfma_f32_16x16x32_bf16 v[70:73], v[150:153], v[210:213], v[70:73]
	v_mfma_f32_16x16x32_bf16 v[66:69], v[158:161], v[210:213], v[66:69]
	s_nop 0
	s_barrier
	s_add_i32 s8, s14, s56
	v_lshl_add_u64 v[214:215], v[214:215], 0, s[4:5]
	s_mov_b32 m0, s8
	ds_read_b128 v[162:165], v238 offset:49152
	ds_read_b128 v[186:189], v238 offset:50176
	ds_read_b128 v[190:193], v238 offset:51200
	ds_read_b128 v[194:197], v238 offset:52224
	ds_read_b128 v[198:201], v238 offset:53248
	ds_read_b128 v[202:205], v238 offset:54272
	ds_read_b128 v[206:209], v238 offset:55296
	ds_read_b128 v[210:213], v238 offset:56320
	global_load_lds_dwordx4 v[214:215], off
	v_lshl_add_u64 v[214:215], v[216:217], 0, s[4:5]
	s_add_i32 m0, s8, 0x2000
	s_add_i32 s8, s15, s56
	global_load_lds_dwordx4 v[214:215], off
	v_lshl_add_u64 v[214:215], v[218:219], 0, s[4:5]
	s_mov_b32 m0, s8
	s_nop 0
	global_load_lds_dwordx4 v[214:215], off
	v_lshl_add_u64 v[214:215], v[220:221], 0, s[4:5]
	s_add_i32 m0, s8, 0x2000
	s_nop 0
	global_load_lds_dwordx4 v[214:215], off
	v_lshl_add_u64 v[214:215], v[222:223], 0, s[4:5]
	s_mov_b32 m0, s69
	s_nop 0
	global_load_lds_dwordx4 v[214:215], off
	v_lshl_add_u64 v[214:215], v[240:241], 0, s[4:5]
	s_mov_b32 m0, s84
	s_nop 0
	global_load_lds_dwordx4 v[214:215], off
	s_waitcnt vmcnt(8)
	s_waitcnt lgkmcnt(0)
	s_barrier
	s_nop 0
	s_waitcnt lgkmcnt(0)
	v_mfma_f32_16x16x32_bf16 v[62:65], v[130:133], v[162:165], v[62:65]
	v_mfma_f32_16x16x32_bf16 v[58:61], v[138:141], v[162:165], v[58:61]
	v_mfma_f32_16x16x32_bf16 v[46:49], v[130:133], v[190:193], v[46:49]
	v_mfma_f32_16x16x32_bf16 v[42:45], v[138:141], v[190:193], v[42:45]
	v_mfma_f32_16x16x32_bf16 v[30:33], v[130:133], v[198:201], v[30:33]
	v_mfma_f32_16x16x32_bf16 v[26:29], v[138:141], v[198:201], v[26:29]
	v_mfma_f32_16x16x32_bf16 v[14:17], v[130:133], v[206:209], v[14:17]
	v_mfma_f32_16x16x32_bf16 v[10:13], v[138:141], v[206:209], v[10:13]
	v_mfma_f32_16x16x32_bf16 v[62:65], v[134:137], v[186:189], v[62:65]
	v_mfma_f32_16x16x32_bf16 v[58:61], v[142:145], v[186:189], v[58:61]
	v_mfma_f32_16x16x32_bf16 v[46:49], v[134:137], v[194:197], v[46:49]
	v_mfma_f32_16x16x32_bf16 v[42:45], v[142:145], v[194:197], v[42:45]
	v_mfma_f32_16x16x32_bf16 v[30:33], v[134:137], v[202:205], v[30:33]
	v_mfma_f32_16x16x32_bf16 v[26:29], v[142:145], v[202:205], v[26:29]
	v_mfma_f32_16x16x32_bf16 v[14:17], v[134:137], v[210:213], v[14:17]
	v_mfma_f32_16x16x32_bf16 v[10:13], v[142:145], v[210:213], v[10:13]
	s_nop 0
	s_nop 0
	v_mfma_f32_16x16x32_bf16 v[54:57], v[146:149], v[162:165], v[54:57]
	v_mfma_f32_16x16x32_bf16 v[50:53], v[154:157], v[162:165], v[50:53]
	v_mfma_f32_16x16x32_bf16 v[38:41], v[146:149], v[190:193], v[38:41]
	v_mfma_f32_16x16x32_bf16 v[34:37], v[154:157], v[190:193], v[34:37]
	v_mfma_f32_16x16x32_bf16 v[22:25], v[146:149], v[198:201], v[22:25]
	v_mfma_f32_16x16x32_bf16 v[18:21], v[154:157], v[198:201], v[18:21]
	v_mfma_f32_16x16x32_bf16 v[6:9], v[146:149], v[206:209], v[6:9]
	v_mfma_f32_16x16x32_bf16 v[2:5], v[154:157], v[206:209], v[2:5]
	v_mfma_f32_16x16x32_bf16 v[54:57], v[150:153], v[186:189], v[54:57]
	v_mfma_f32_16x16x32_bf16 v[50:53], v[158:161], v[186:189], v[50:53]
	v_mfma_f32_16x16x32_bf16 v[38:41], v[150:153], v[194:197], v[38:41]
	v_mfma_f32_16x16x32_bf16 v[34:37], v[158:161], v[194:197], v[34:37]
	v_mfma_f32_16x16x32_bf16 v[22:25], v[150:153], v[202:205], v[22:25]
	v_mfma_f32_16x16x32_bf16 v[18:21], v[158:161], v[202:205], v[18:21]
	v_mfma_f32_16x16x32_bf16 v[6:9], v[150:153], v[210:213], v[6:9]
	v_mfma_f32_16x16x32_bf16 v[2:5], v[158:161], v[210:213], v[2:5]
	s_nop 0
	s_add_u32 s2, s2, 0x100
	s_addc_u32 s3, s3, 0
	s_add_u32 s10, s10, 0x100
	s_addc_u32 s11, s11, 0
	s_barrier
	s_cmp_ge_u32 s13, s66
	s_mov_b32 s8, s13
	s_cbranch_scc0 .LBB0_394
	s_and_b64 vcc, exec, s[94:95]
	s_cbranch_vccz .LBB0_397
	s_barrier
